# decdefer: FFN-in next-unit decode (integer-division chain) moved from the tile top into the load part of segment 3 of the peeled first K iteration; on top of itemwait
# baseline (speedup 1.0000x reference)
.LBB0_995:
	s_add_i32 s49, s49, 1
	s_mul_i32 s6, s49, s48
	s_mul_hi_u32 s7, s49, s60
	s_add_i32 s7, s7, s6
	s_mul_i32 s6, s49, s60
	s_add_u32 s18, s6, s94
	s_addc_u32 s19, s7, s39
	v_mov_b64_e32 v[2:3], s[80:81]
	v_cmp_ge_i64_e32 vcc, s[18:19], v[2:3]
	v_cmp_lt_i64_e64 s[6:7], s[18:19], v[2:3]
	s_mov_b64 s[98:99], s[24:25]
	s_mov_b64 s[100:101], s[28:29]
	s_add_u32 s53, s24, 0x100
	s_addc_u32 s61, s25, 0
	s_add_u32 s24, s28, 0x40080
	s_addc_u32 s25, s29, 0
	s_mov_b32 s62, -2
	s_add_u32 s28, s24, 0xfffc0080
	s_addc_u32 s29, s25, -1
	s_add_i32 s63, 0, 0x10000
	s_cmp_eq_u32 s62, 12
	s_cselect_b32 s31, s17, s29
	s_cselect_b32 s30, s51, s28
	v_add_u32_e32 v140, s63, v143
	s_cselect_b32 s29, s15, s61
	s_cselect_b32 s28, s52, s53
	s_add_i32 s72, 0, 0x14000
	ds_read_b128 v[146:149], v140
	ds_read_b128 v[150:153], v140 offset:1024
	ds_read_b128 v[154:157], v140 offset:2048
	ds_read_b128 v[158:161], v140 offset:3072
	v_add_u32_e32 v140, s72, v143
	ds_read_b128 v[162:165], v140
	ds_read_b128 v[166:169], v140 offset:1024
	ds_read_b128 v[170:173], v140 offset:2048
	ds_read_b128 v[174:177], v140 offset:3072
	v_lshl_add_u64 v[140:141], s[24:25], 0, v[138:139]
	s_add_i32 m0, s23, 0xc000
	ds_read_b128 v[178:181], v145
	ds_read_b128 v[182:185], v145 offset:1024
	ds_read_b128 v[186:189], v145 offset:2048
	ds_read_b128 v[190:193], v145 offset:3072
	ds_read_b128 v[194:197], v145 offset:4096
	ds_read_b128 v[198:201], v145 offset:5120
	ds_read_b128 v[202:205], v145 offset:6144
	ds_read_b128 v[206:209], v145 offset:7168
	global_load_lds_dwordx4 v[140:141], off
	v_lshl_add_u64 v[140:141], s[24:25], 0, v[136:137]
	s_add_i32 m0, s23, 0xe000
	s_nop 0
	global_load_lds_dwordx4 v[140:141], off
	s_waitcnt vmcnt(8)
	s_waitcnt lgkmcnt(0)
	s_barrier
	s_setprio 1
	s_waitcnt lgkmcnt(0)
	v_mfma_f32_16x16x32_bf16 v[126:129], v[146:149], v[178:181], 0
	v_mfma_f32_16x16x32_bf16 v[122:125], v[154:157], v[178:181], 0
	v_mfma_f32_16x16x32_bf16 v[110:113], v[146:149], v[186:189], 0
	v_mfma_f32_16x16x32_bf16 v[106:109], v[154:157], v[186:189], 0
	v_mfma_f32_16x16x32_bf16 v[94:97], v[146:149], v[194:197], 0
	v_mfma_f32_16x16x32_bf16 v[90:93], v[154:157], v[194:197], 0
	v_mfma_f32_16x16x32_bf16 v[78:81], v[146:149], v[202:205], 0
	v_mfma_f32_16x16x32_bf16 v[74:77], v[154:157], v[202:205], 0
	v_mfma_f32_16x16x32_bf16 v[126:129], v[150:153], v[182:185], v[126:129]
	v_mfma_f32_16x16x32_bf16 v[122:125], v[158:161], v[182:185], v[122:125]
	v_mfma_f32_16x16x32_bf16 v[110:113], v[150:153], v[190:193], v[110:113]
	v_mfma_f32_16x16x32_bf16 v[106:109], v[158:161], v[190:193], v[106:109]
	v_mfma_f32_16x16x32_bf16 v[94:97], v[150:153], v[198:201], v[94:97]
	v_mfma_f32_16x16x32_bf16 v[90:93], v[158:161], v[198:201], v[90:93]
	v_mfma_f32_16x16x32_bf16 v[78:81], v[150:153], v[206:209], v[78:81]
	v_mfma_f32_16x16x32_bf16 v[74:77], v[158:161], v[206:209], v[74:77]
	s_setprio 0
	s_setprio 1
	v_mfma_f32_16x16x32_bf16 v[118:121], v[162:165], v[178:181], 0
	v_mfma_f32_16x16x32_bf16 v[114:117], v[170:173], v[178:181], 0
	v_mfma_f32_16x16x32_bf16 v[102:105], v[162:165], v[186:189], 0
	v_mfma_f32_16x16x32_bf16 v[98:101], v[170:173], v[186:189], 0
	v_mfma_f32_16x16x32_bf16 v[86:89], v[162:165], v[194:197], 0
	v_mfma_f32_16x16x32_bf16 v[82:85], v[170:173], v[194:197], 0
	v_mfma_f32_16x16x32_bf16 v[70:73], v[162:165], v[202:205], 0
	v_mfma_f32_16x16x32_bf16 v[66:69], v[170:173], v[202:205], 0
	v_mfma_f32_16x16x32_bf16 v[118:121], v[166:169], v[182:185], v[118:121]
	v_mfma_f32_16x16x32_bf16 v[114:117], v[174:177], v[182:185], v[114:117]
	v_mfma_f32_16x16x32_bf16 v[102:105], v[166:169], v[190:193], v[102:105]
	v_mfma_f32_16x16x32_bf16 v[98:101], v[174:177], v[190:193], v[98:101]
	v_mfma_f32_16x16x32_bf16 v[86:89], v[166:169], v[198:201], v[86:89]
	v_mfma_f32_16x16x32_bf16 v[82:85], v[174:177], v[198:201], v[82:85]
	v_mfma_f32_16x16x32_bf16 v[70:73], v[166:169], v[206:209], v[70:73]
	v_mfma_f32_16x16x32_bf16 v[66:69], v[174:177], v[206:209], v[66:69]
	s_setprio 0
	s_barrier
	s_add_i32 s63, s63, s40
	v_lshl_add_u64 v[140:141], s[28:29], 0, v[0:1]
	s_mov_b32 m0, s63
	ds_read_b128 v[178:181], v145 offset:16384
	ds_read_b128 v[182:185], v145 offset:17408
	ds_read_b128 v[186:189], v145 offset:18432
	ds_read_b128 v[190:193], v145 offset:19456
	ds_read_b128 v[194:197], v145 offset:20480
	ds_read_b128 v[198:201], v145 offset:21504
	ds_read_b128 v[202:205], v145 offset:22528
	ds_read_b128 v[206:209], v145 offset:23552
	global_load_lds_dwordx4 v[140:141], off
	s_add_i32 m0, s63, 0x2000
	s_add_u32 s70, s28, 0x40000
	v_lshl_add_u64 v[210:211], s[28:29], 0, v[134:135]
	s_addc_u32 s71, s29, 0
	s_add_i32 s63, s72, s40
	global_load_lds_dwordx4 v[210:211], off
	v_lshl_add_u64 v[212:213], s[70:71], 0, v[0:1]
	s_mov_b32 m0, s63
	v_lshl_add_u64 v[214:215], s[30:31], 0, v[132:133]
	global_load_lds_dwordx4 v[212:213], off
	v_lshl_add_u64 v[212:213], s[70:71], 0, v[134:135]
	s_add_i32 m0, s63, 0x2000
	s_nop 0
	global_load_lds_dwordx4 v[212:213], off
	v_lshl_add_u64 v[212:213], s[30:31], 0, v[130:131]
	s_mov_b32 m0, s23
	s_nop 0
	global_load_lds_dwordx4 v[212:213], off
	s_mov_b32 m0, s43
	s_nop 0
	global_load_lds_dwordx4 v[214:215], off
	s_waitcnt vmcnt(8)
	s_waitcnt lgkmcnt(0)
	s_barrier
	s_setprio 1
	s_waitcnt lgkmcnt(0)
	v_mfma_f32_16x16x32_bf16 v[62:65], v[146:149], v[178:181], 0
	v_mfma_f32_16x16x32_bf16 v[58:61], v[154:157], v[178:181], 0
	v_mfma_f32_16x16x32_bf16 v[46:49], v[146:149], v[186:189], 0
	v_mfma_f32_16x16x32_bf16 v[42:45], v[154:157], v[186:189], 0
	v_mfma_f32_16x16x32_bf16 v[30:33], v[146:149], v[194:197], 0
	v_mfma_f32_16x16x32_bf16 v[26:29], v[154:157], v[194:197], 0
	v_mfma_f32_16x16x32_bf16 v[14:17], v[146:149], v[202:205], 0
	v_mfma_f32_16x16x32_bf16 v[10:13], v[154:157], v[202:205], 0
	v_mfma_f32_16x16x32_bf16 v[62:65], v[150:153], v[182:185], v[62:65]
	v_mfma_f32_16x16x32_bf16 v[58:61], v[158:161], v[182:185], v[58:61]
	v_mfma_f32_16x16x32_bf16 v[46:49], v[150:153], v[190:193], v[46:49]
	v_mfma_f32_16x16x32_bf16 v[42:45], v[158:161], v[190:193], v[42:45]
	v_mfma_f32_16x16x32_bf16 v[30:33], v[150:153], v[198:201], v[30:33]
	v_mfma_f32_16x16x32_bf16 v[26:29], v[158:161], v[198:201], v[26:29]
	v_mfma_f32_16x16x32_bf16 v[14:17], v[150:153], v[206:209], v[14:17]
	v_mfma_f32_16x16x32_bf16 v[10:13], v[158:161], v[206:209], v[10:13]
	s_setprio 0
	s_setprio 1
	v_mfma_f32_16x16x32_bf16 v[54:57], v[162:165], v[178:181], 0
	v_mfma_f32_16x16x32_bf16 v[50:53], v[170:173], v[178:181], 0
	v_mfma_f32_16x16x32_bf16 v[38:41], v[162:165], v[186:189], 0
	v_mfma_f32_16x16x32_bf16 v[34:37], v[170:173], v[186:189], 0
	v_mfma_f32_16x16x32_bf16 v[22:25], v[162:165], v[194:197], 0
	v_mfma_f32_16x16x32_bf16 v[18:21], v[170:173], v[194:197], 0
	v_mfma_f32_16x16x32_bf16 v[6:9], v[162:165], v[202:205], 0
	v_mfma_f32_16x16x32_bf16 v[2:5], v[170:173], v[202:205], 0
	v_mfma_f32_16x16x32_bf16 v[54:57], v[166:169], v[182:185], v[54:57]
	v_mfma_f32_16x16x32_bf16 v[50:53], v[174:177], v[182:185], v[50:53]
	v_mfma_f32_16x16x32_bf16 v[38:41], v[166:169], v[190:193], v[38:41]
	v_mfma_f32_16x16x32_bf16 v[34:37], v[174:177], v[190:193], v[34:37]
	v_mfma_f32_16x16x32_bf16 v[22:25], v[166:169], v[198:201], v[22:25]
	v_mfma_f32_16x16x32_bf16 v[18:21], v[174:177], v[198:201], v[18:21]
	v_mfma_f32_16x16x32_bf16 v[6:9], v[166:169], v[206:209], v[6:9]
	v_mfma_f32_16x16x32_bf16 v[2:5], v[174:177], v[206:209], v[2:5]
	s_setprio 0
	s_barrier
	s_add_i32 s63, 0, 0x18000
	s_add_i32 s70, 0, 0x1c000
	v_add_u32_e32 v158, s63, v143
	v_add_u32_e32 v174, s70, v143
	ds_read_b128 v[146:149], v158
	ds_read_b128 v[150:153], v158 offset:1024
	ds_read_b128 v[154:157], v158 offset:2048
	ds_read_b128 v[158:161], v158 offset:3072
	ds_read_b128 v[162:165], v174
	ds_read_b128 v[166:169], v174 offset:1024
	ds_read_b128 v[170:173], v174 offset:2048
	ds_read_b128 v[174:177], v174 offset:3072
	s_add_u32 s30, s30, 0x40000
	s_addc_u32 s31, s31, 0
	s_mov_b32 m0, s44
	v_lshl_add_u64 v[216:217], s[30:31], 0, v[130:131]
	ds_read_b128 v[178:181], v145 offset:32768
	ds_read_b128 v[182:185], v145 offset:33792
	ds_read_b128 v[186:189], v145 offset:34816
	ds_read_b128 v[190:193], v145 offset:35840
	ds_read_b128 v[194:197], v145 offset:36864
	ds_read_b128 v[198:201], v145 offset:37888
	ds_read_b128 v[202:205], v145 offset:38912
	ds_read_b128 v[206:209], v145 offset:39936
	global_load_lds_dwordx4 v[216:217], off
	v_lshl_add_u64 v[216:217], s[30:31], 0, v[132:133]
	s_mov_b32 m0, s45
	s_nop 0
	global_load_lds_dwordx4 v[216:217], off
	s_andn2_b64 vcc, exec, s[6:7]
	s_cbranch_vccnz .LBB0_1001
	s_ashr_i32 s14, s18, 31
	s_lshr_b32 s14, s14, 29
	s_add_i32 s16, s18, s14
	s_and_b32 s14, s16, -8
	s_sub_i32 s17, s18, s14
	s_cmp_ge_i32 s17, s36
	s_mov_b64 s[14:15], -1
	s_cbranch_scc0 .LBB0_998
	s_sub_i32 s14, s17, s36
	s_mul_i32 s14, s14, s35
	s_add_i32 s18, s14, s38
	s_mov_b64 s[14:15], 0

.LBB0_1000:
	s_ashr_i32 s14, s16, 3
	s_add_i32 s14, s18, s14
	s_mul_hi_i32 s15, s14, 0x2e8ba2e9
	s_lshr_b32 s16, s15, 31
	s_ashr_i32 s15, s15, 5
	s_add_i32 s15, s15, s16
	s_lshl_b32 s16, s15, 3
	s_sub_i32 s17, s34, s16
	s_min_i32 s17, s17, 8
	s_abs_i32 s18, s17
	v_cvt_f32_u32_e32 v236, s18
	s_sub_i32 s20, 0, s18
	s_mulk_i32 s15, 0xb0
	s_sub_i32 s15, s14, s15
	v_rcp_iflag_f32_e32 v236, v236
	s_abs_i32 s14, s15
	s_xor_b32 s19, s15, s17
	s_ashr_i32 s19, s19, 31
	v_mul_f32_e32 v236, 0x4f7ffffe, v236
	v_cvt_u32_f32_e32 v236, v236
	s_nop 0
	v_readfirstlane_b32 s21, v236
	s_mul_i32 s20, s20, s21
	s_mul_hi_u32 s20, s21, s20
	s_add_i32 s21, s21, s20
	s_mul_hi_u32 s20, s14, s21
	s_mul_i32 s21, s20, s18
	s_sub_i32 s14, s14, s21
	s_add_i32 s30, s20, 1
	s_sub_i32 s21, s14, s18
	s_cmp_ge_u32 s14, s18
	s_cselect_b32 s20, s30, s20
	s_cselect_b32 s14, s21, s14
	s_add_i32 s21, s20, 1
	s_cmp_ge_u32 s14, s18
	s_cselect_b32 s14, s21, s20
	s_xor_b32 s14, s14, s19
	s_sub_i32 s14, s14, s19
	s_mul_i32 s17, s14, s17
	s_sub_i32 s15, s15, s17
	s_add_i32 s16, s16, s15
.LBB0_1001:
	s_ashr_i32 s17, s16, 31
	s_lshl_b64 s[18:19], s[16:17], 19
	s_add_u32 s18, s92, s18
	s_addc_u32 s19, s93, s19
	s_and_b64 s[20:21], s[6:7], exec
	s_cselect_b32 s17, s19, s101
	s_cselect_b32 s51, s18, s100
	s_ashr_i32 s15, s14, 31
	s_lshl_b64 s[20:21], s[14:15], 19
	s_add_u32 s20, s41, s20
	s_addc_u32 s21, s42, s21
	s_and_b64 vcc, s[6:7], exec
	s_cselect_b32 s15, s21, s99
	s_cselect_b32 s52, s20, s98
	s_waitcnt vmcnt(8)
	s_waitcnt lgkmcnt(0)
	s_barrier
	s_setprio 1
	s_waitcnt lgkmcnt(0)
	v_mfma_f32_16x16x32_bf16 v[126:129], v[146:149], v[178:181], v[126:129]
	v_mfma_f32_16x16x32_bf16 v[122:125], v[154:157], v[178:181], v[122:125]
	v_mfma_f32_16x16x32_bf16 v[110:113], v[146:149], v[186:189], v[110:113]
	v_mfma_f32_16x16x32_bf16 v[106:109], v[154:157], v[186:189], v[106:109]
	v_mfma_f32_16x16x32_bf16 v[94:97], v[146:149], v[194:197], v[94:97]
	v_mfma_f32_16x16x32_bf16 v[90:93], v[154:157], v[194:197], v[90:93]
	v_mfma_f32_16x16x32_bf16 v[78:81], v[146:149], v[202:205], v[78:81]
	v_mfma_f32_16x16x32_bf16 v[74:77], v[154:157], v[202:205], v[74:77]
	v_mfma_f32_16x16x32_bf16 v[126:129], v[150:153], v[182:185], v[126:129]
	v_mfma_f32_16x16x32_bf16 v[122:125], v[158:161], v[182:185], v[122:125]
	v_mfma_f32_16x16x32_bf16 v[110:113], v[150:153], v[190:193], v[110:113]
	v_mfma_f32_16x16x32_bf16 v[106:109], v[158:161], v[190:193], v[106:109]
	v_mfma_f32_16x16x32_bf16 v[94:97], v[150:153], v[198:201], v[94:97]
	v_mfma_f32_16x16x32_bf16 v[90:93], v[158:161], v[198:201], v[90:93]
	v_mfma_f32_16x16x32_bf16 v[78:81], v[150:153], v[206:209], v[78:81]
	v_mfma_f32_16x16x32_bf16 v[74:77], v[158:161], v[206:209], v[74:77]
	s_setprio 0
	s_setprio 1
	v_mfma_f32_16x16x32_bf16 v[118:121], v[162:165], v[178:181], v[118:121]
	v_mfma_f32_16x16x32_bf16 v[114:117], v[170:173], v[178:181], v[114:117]
	v_mfma_f32_16x16x32_bf16 v[102:105], v[162:165], v[186:189], v[102:105]
	v_mfma_f32_16x16x32_bf16 v[98:101], v[170:173], v[186:189], v[98:101]
	v_mfma_f32_16x16x32_bf16 v[86:89], v[162:165], v[194:197], v[86:89]
	v_mfma_f32_16x16x32_bf16 v[82:85], v[170:173], v[194:197], v[82:85]
	v_mfma_f32_16x16x32_bf16 v[70:73], v[162:165], v[202:205], v[70:73]
	v_mfma_f32_16x16x32_bf16 v[66:69], v[170:173], v[202:205], v[66:69]
	v_mfma_f32_16x16x32_bf16 v[118:121], v[166:169], v[182:185], v[118:121]
	v_mfma_f32_16x16x32_bf16 v[114:117], v[174:177], v[182:185], v[114:117]
	v_mfma_f32_16x16x32_bf16 v[102:105], v[166:169], v[190:193], v[102:105]
	v_mfma_f32_16x16x32_bf16 v[98:101], v[174:177], v[190:193], v[98:101]
	v_mfma_f32_16x16x32_bf16 v[86:89], v[166:169], v[198:201], v[86:89]
	v_mfma_f32_16x16x32_bf16 v[82:85], v[174:177], v[198:201], v[82:85]
	v_mfma_f32_16x16x32_bf16 v[70:73], v[166:169], v[206:209], v[70:73]
	v_mfma_f32_16x16x32_bf16 v[66:69], v[174:177], v[206:209], v[66:69]
	s_setprio 0
	s_barrier
	s_add_i32 s30, s63, s40
	v_lshl_add_u64 v[140:141], v[140:141], 0, s[76:77]
	s_mov_b32 m0, s30
	ds_read_b128 v[178:181], v145 offset:49152
	ds_read_b128 v[182:185], v145 offset:50176
	ds_read_b128 v[186:189], v145 offset:51200
	ds_read_b128 v[190:193], v145 offset:52224
	ds_read_b128 v[194:197], v145 offset:53248
	ds_read_b128 v[198:201], v145 offset:54272
	ds_read_b128 v[202:205], v145 offset:55296
	ds_read_b128 v[206:209], v145 offset:56320
	global_load_lds_dwordx4 v[140:141], off
	s_add_i32 m0, s30, 0x2000
	s_add_u32 s28, s28, 0x40080
	v_lshl_add_u64 v[140:141], v[210:211], 0, s[76:77]
	s_addc_u32 s29, s29, 0
	s_add_i32 s30, s70, s40
	global_load_lds_dwordx4 v[140:141], off
	v_lshl_add_u64 v[140:141], s[28:29], 0, v[0:1]
	s_mov_b32 m0, s30
	s_nop 0
	global_load_lds_dwordx4 v[140:141], off
	v_lshl_add_u64 v[140:141], s[28:29], 0, v[134:135]
	s_add_i32 m0, s30, 0x2000
	s_nop 0
	global_load_lds_dwordx4 v[140:141], off
	v_lshl_add_u64 v[140:141], v[212:213], 0, s[76:77]
	s_mov_b32 m0, s46
	s_nop 0
	global_load_lds_dwordx4 v[140:141], off
	v_lshl_add_u64 v[140:141], v[214:215], 0, s[76:77]
	s_mov_b32 m0, s47
	s_nop 0
	global_load_lds_dwordx4 v[140:141], off
	s_waitcnt vmcnt(8)
	s_waitcnt lgkmcnt(0)
	s_barrier
	s_setprio 1
	s_waitcnt lgkmcnt(0)
	v_mfma_f32_16x16x32_bf16 v[62:65], v[146:149], v[178:181], v[62:65]
	v_mfma_f32_16x16x32_bf16 v[58:61], v[154:157], v[178:181], v[58:61]
	v_mfma_f32_16x16x32_bf16 v[46:49], v[146:149], v[186:189], v[46:49]
	v_mfma_f32_16x16x32_bf16 v[42:45], v[154:157], v[186:189], v[42:45]
	v_mfma_f32_16x16x32_bf16 v[30:33], v[146:149], v[194:197], v[30:33]
	v_mfma_f32_16x16x32_bf16 v[26:29], v[154:157], v[194:197], v[26:29]
	v_mfma_f32_16x16x32_bf16 v[14:17], v[146:149], v[202:205], v[14:17]
	v_mfma_f32_16x16x32_bf16 v[10:13], v[154:157], v[202:205], v[10:13]
	v_mfma_f32_16x16x32_bf16 v[62:65], v[150:153], v[182:185], v[62:65]
	v_mfma_f32_16x16x32_bf16 v[58:61], v[158:161], v[182:185], v[58:61]
	v_mfma_f32_16x16x32_bf16 v[46:49], v[150:153], v[190:193], v[46:49]
	v_mfma_f32_16x16x32_bf16 v[42:45], v[158:161], v[190:193], v[42:45]
	v_mfma_f32_16x16x32_bf16 v[30:33], v[150:153], v[198:201], v[30:33]
	v_mfma_f32_16x16x32_bf16 v[26:29], v[158:161], v[198:201], v[26:29]
	v_mfma_f32_16x16x32_bf16 v[14:17], v[150:153], v[206:209], v[14:17]
	v_mfma_f32_16x16x32_bf16 v[10:13], v[158:161], v[206:209], v[10:13]
	s_setprio 0
	s_setprio 1
	v_mfma_f32_16x16x32_bf16 v[54:57], v[162:165], v[178:181], v[54:57]
	v_mfma_f32_16x16x32_bf16 v[50:53], v[170:173], v[178:181], v[50:53]
	v_mfma_f32_16x16x32_bf16 v[38:41], v[162:165], v[186:189], v[38:41]
	v_mfma_f32_16x16x32_bf16 v[34:37], v[170:173], v[186:189], v[34:37]
	v_mfma_f32_16x16x32_bf16 v[22:25], v[162:165], v[194:197], v[22:25]
	v_mfma_f32_16x16x32_bf16 v[18:21], v[170:173], v[194:197], v[18:21]
	v_mfma_f32_16x16x32_bf16 v[6:9], v[162:165], v[202:205], v[6:9]
	v_mfma_f32_16x16x32_bf16 v[2:5], v[170:173], v[202:205], v[2:5]
	v_mfma_f32_16x16x32_bf16 v[54:57], v[166:169], v[182:185], v[54:57]
	v_mfma_f32_16x16x32_bf16 v[50:53], v[174:177], v[182:185], v[50:53]
	v_mfma_f32_16x16x32_bf16 v[38:41], v[166:169], v[190:193], v[38:41]
	v_mfma_f32_16x16x32_bf16 v[34:37], v[174:177], v[190:193], v[34:37]
	v_mfma_f32_16x16x32_bf16 v[22:25], v[166:169], v[198:201], v[22:25]
	v_mfma_f32_16x16x32_bf16 v[18:21], v[174:177], v[198:201], v[18:21]
	v_mfma_f32_16x16x32_bf16 v[6:9], v[166:169], v[206:209], v[6:9]
	v_mfma_f32_16x16x32_bf16 v[2:5], v[174:177], v[206:209], v[2:5]
	s_setprio 0
	s_barrier
	s_add_i32 s62, s62, 2
	s_add_u32 s53, s53, 0x100
	s_addc_u32 s61, s61, 0
	s_add_u32 s24, s24, 0x100
	s_addc_u32 s25, s25, 0
	s_cmp_gt_u32 s62, 13
